# GLA chain: silu(gate) factors of the next block computed four instructions at a time behind the state-update and output MFMAs of the current block; block head reduced to the two multiplies and the con
# speedup vs baseline: 1.0173x; 1.0014x over previous
.LBB0_1085:
	s_or_b64 exec, exec, s[8:9]
	s_waitcnt vmcnt(18)
	v_pk_mul_f32 v[110:111], v[20:21], v[110:111]
	v_pk_mul_f32 v[108:109], v[22:23], v[108:109]
	v_pk_mul_f32 v[106:107], v[16:17], v[106:107]
	v_pk_mul_f32 v[104:105], v[18:19], v[104:105]
	s_mov_b32 s8, 0x12880000
	s_mov_b64 s[38:39], 0xc0000
	s_add_i32 s22, s22, 3
	v_lshl_add_u64 v[126:127], v[126:127], 0, s[38:39]
	v_add_u32_e32 v161, 0x600, v161
	v_lshl_add_u64 v[122:123], v[122:123], 0, s[38:39]
	s_cmp_gt_u32 s31, 28
	v_pk_mul_f32 v[110:111], v[198:199], v[110:111]
	v_pk_mul_f32 v[108:109], v[200:201], v[108:109]
	v_pk_mul_f32 v[106:107], v[202:203], v[106:107]
	v_pk_mul_f32 v[104:105], v[204:205], v[104:105]
	v_cvt_pk_bf16_f32 v100, v110, v111
	v_cvt_pk_bf16_f32 v101, v108, v109
	v_cvt_pk_bf16_f32 v102, v106, v107
	v_cvt_pk_bf16_f32 v103, v104, v105
	s_mov_b64 s[8:9], 0xc000
	s_nop 0
	s_add_u32 s44, s6, 0x127c0000
	s_addc_u32 s45, s7, 0
	global_store_dwordx4 v122, v[100:103], s[44:45]
	s_waitcnt lgkmcnt(0)
	s_barrier
	v_lshl_add_u64 v[124:125], v[124:125], 0, s[8:9]
	v_lshl_add_u64 v[128:129], v[128:129], 0, s[8:9]
	v_lshl_add_u64 v[130:131], v[130:131], 0, s[8:9]
	s_mov_b64 s[8:9], 0x3000
	v_lshl_add_u64 v[120:121], v[120:121], 0, s[8:9]
	s_cmp_gt_u32 s31, 28
	s_cbranch_scc1 .LBB0_1092
.LBB0_1086:
	s_and_b32 s40, s22, 1
	s_mul_i32 s8, s40, 0x6c00
	v_readlane_b32 s38, v254, 54
	s_add_i32 s41, s38, s8
	v_add_u32_e32 v100, s41, v146
	v_lshl_add_u64 v[132:133], s[6:7], 0, v[124:125]
	ds_write_b128 v100, v[24:27]
	ds_write_b128 v100, v[28:31] offset:9216
	ds_write_b128 v100, v[32:35] offset:18432
	v_lshl_add_u64 v[136:137], s[6:7], 0, v[128:129]
	s_nop 0
	s_mov_b32 s8, 0xb40c000
	v_lshl_add_u64 v[138:139], s[6:7], 0, v[126:127]
	s_nop 0
	v_lshl_add_u64 v[140:141], s[6:7], 0, v[130:131]
	s_add_u32 s44, s6, 0x0
	s_addc_u32 s45, s7, 0
	global_load_dwordx4 v[24:27], v124, s[44:45]
	s_nop 0
	s_add_u32 s44, s6, 0x2000
	s_addc_u32 s45, s7, 0
	global_load_dwordx4 v[28:31], v124, s[44:45]
	s_nop 0
	s_add_u32 s44, s6, 0xb40c000
	s_addc_u32 s45, s7, 0
	global_load_dwordx4 v[116:119], v128, s[44:45]
	global_load_dwordx4 v[112:115], v128, s[44:45] offset:64
	global_load_dwordx4 v[108:111], v128, s[44:45] offset:128
	global_load_dwordx4 v[104:107], v128, s[44:45] offset:192
	s_nop 0
	s_add_u32 s44, s6, 0x0
	s_addc_u32 s45, s7, 0
	global_load_dwordx4 v[32:35], v126, s[44:45]
	s_add_u32 s44, s6, 0x0
	s_addc_u32 s45, s7, 0
	global_load_dwordx4 v[100:103], v130, s[44:45]
	s_add_i32 s31, s22, -1
	s_and_b32 s8, s31, 1
	s_mul_i32 s9, s8, 0x6c00
	s_add_i32 s38, s38, s9
	v_mov_b32_e32 v134, s38
	ds_read_b128 v[162:165], v161
	ds_read_b128 v[166:169], v161 offset:32
	ds_read_b128 v[170:173], v161 offset:64
	ds_read_b128 v[174:177], v161 offset:96
	s_waitcnt lgkmcnt(3)
	v_pk_mul_f32 v[2:3], v[2:3], v[164:165]
	v_add_u32_e32 v135, v134, v147
	v_add_u32_e32 v134, v134, v145
	ds_read_b128 v[178:181], v135
	ds_read_b128 v[182:185], v134 offset:18432
	s_waitcnt lgkmcnt(2)
	v_pk_mul_f32 v[14:15], v[14:15], v[176:177]
	v_pk_mul_f32 v[10:11], v[10:11], v[172:173]
	v_pk_mul_f32 v[6:7], v[6:7], v[168:169]
	v_pk_mul_f32 v[12:13], v[12:13], v[174:175]
	v_pk_mul_f32 v[8:9], v[8:9], v[170:171]
	v_pk_mul_f32 v[4:5], v[4:5], v[166:167]
	v_pk_mul_f32 v[0:1], v[0:1], v[162:163]
	ds_read_b128 v[162:165], v135 offset:32
	ds_read_b128 v[166:169], v134 offset:18464
	s_waitcnt lgkmcnt(2)
	v_mfma_f32_32x32x16_bf16 v[0:15], v[178:181], v[182:185], v[0:15]
	s_waitcnt vmcnt(14)
	v_lshlrev_b32_e32 v198, 16, v40
	v_lshlrev_b32_e32 v200, 16, v41
	v_lshlrev_b32_e32 v202, 16, v42
	v_lshlrev_b32_e32 v204, 16, v43
	s_mul_i32 s9, s8, 0x4400
	s_add_i32 s42, s9, 0
	s_xor_b32 s39, s8, 1
	s_mul_i32 s9, s39, 0x4400
	s_waitcnt lgkmcnt(0)
	v_mfma_f32_32x32x16_bf16 v[0:15], v[162:165], v[166:169], v[0:15]
	v_and_b32_e32 v199, 0xffff0000, v40
	v_and_b32_e32 v201, 0xffff0000, v41
	v_and_b32_e32 v203, 0xffff0000, v42
	v_and_b32_e32 v205, 0xffff0000, v43
	ds_read_b128 v[162:165], v135 offset:64
	ds_read_b128 v[166:169], v134 offset:18496
	ds_read_b128 v[170:173], v135 offset:96
	ds_read_b128 v[174:177], v134 offset:18528
	v_add_u32_e32 v134, s42, v150
	s_waitcnt lgkmcnt(2)
	v_mfma_f32_32x32x16_bf16 v[0:15], v[162:165], v[166:169], v[0:15]
	v_mul_f32_e32 v214, 0xbfb8aa3b, v198
	v_mul_f32_e32 v215, 0xbfb8aa3b, v200
	v_mul_f32_e32 v216, 0xbfb8aa3b, v202
	v_mul_f32_e32 v217, 0xbfb8aa3b, v204
	v_add_u32_e32 v162, 0x6000, v134
	v_mov_b32_e32 v158, v162
	s_waitcnt lgkmcnt(0)
	v_mfma_f32_32x32x16_bf16 v[0:15], v[170:173], v[174:177], v[0:15]
	v_mul_f32_e32 v218, 0xbfb8aa3b, v199
	v_mul_f32_e32 v219, 0xbfb8aa3b, v201
	v_mul_f32_e32 v220, 0xbfb8aa3b, v203
	v_mul_f32_e32 v221, 0xbfb8aa3b, v205
	s_nop 11
	v_cvt_pk_bf16_f32 v134, v0, v1
	v_cvt_pk_bf16_f32 v135, v2, v3
	v_cvt_pk_bf16_f32 v142, v4, v5
	v_cvt_pk_bf16_f32 v143, v6, v7
	ds_write2_b64 v158, v[134:135], v[142:143] offset1:2
	v_cvt_pk_bf16_f32 v134, v8, v9
	v_cvt_pk_bf16_f32 v135, v10, v11
	v_cvt_pk_bf16_f32 v142, v12, v13
	v_cvt_pk_bf16_f32 v143, v14, v15
	ds_write2_b64 v158, v[134:135], v[142:143] offset0:4 offset1:6
	v_add_u32_e32 v134, s9, v152
	v_add_u32_e32 v164, 0x6000, v134
	v_mov_b32_e32 v134, v164
	ds_read_b128 v[166:169], v134
	ds_read_b128 v[170:173], v134 offset:64
	ds_read_b128 v[174:177], v134 offset:4352
	ds_read_b128 v[178:181], v134 offset:4416
	ds_read_b128 v[182:185], v134 offset:128
	ds_read_b128 v[186:189], v134 offset:192
	ds_read_b128 v[190:193], v134 offset:4480
	ds_read_b128 v[194:197], v134 offset:4544
	v_lshl_add_u64 v[134:135], s[6:7], 0, v[120:121]
	s_waitcnt vmcnt(20) lgkmcnt(7)
	v_mfma_f32_16x16x32_bf16 v[166:169], v[80:83], v[166:169], 0
	v_exp_f32_e32 v214, v214
	v_exp_f32_e32 v215, v215
	v_exp_f32_e32 v216, v216
	v_exp_f32_e32 v217, v217
	s_mul_i32 s9, s39, 0x4100
	v_add_u32_e32 v142, s9, v157
	v_add_u32_e32 v163, 0xe800, v142
	s_waitcnt lgkmcnt(5)
	v_mfma_f32_16x16x32_bf16 v[80:83], v[80:83], v[174:177], 0
	v_exp_f32_e32 v218, v218
	v_exp_f32_e32 v219, v219
	v_exp_f32_e32 v220, v220
	v_exp_f32_e32 v221, v221
	v_mov_b32_e32 v142, v163
	s_mulk_i32 s8, 0xfd00
	s_waitcnt vmcnt(19)
	v_mfma_f32_16x16x32_bf16 v[166:169], v[76:79], v[170:173], v[166:169]
	v_add_f32_e32 v214, 1.0, v214
	v_add_f32_e32 v215, 1.0, v215
	v_add_f32_e32 v216, 1.0, v216
	v_add_f32_e32 v217, 1.0, v217
	s_add_i32 s43, s42, s8
	v_lshlrev_b32_e32 v158, 2, v144
	s_mov_b32 s8, 0xe800
	s_waitcnt lgkmcnt(4)
	v_mfma_f32_16x16x32_bf16 v[76:79], v[76:79], v[178:181], v[80:83]
	v_add_f32_e32 v218, 1.0, v218
	v_add_f32_e32 v219, 1.0, v219
	v_add_f32_e32 v220, 1.0, v220
	v_add_f32_e32 v221, 1.0, v221
	s_waitcnt vmcnt(18) lgkmcnt(3)
	v_mfma_f32_16x16x32_bf16 v[80:83], v[72:75], v[182:185], v[166:169]
	v_rcp_f32_e32 v206, v214
	v_rcp_f32_e32 v212, v215
	v_rcp_f32_e32 v222, v216
	v_rcp_f32_e32 v224, v217
	s_waitcnt lgkmcnt(1)
	v_mfma_f32_16x16x32_bf16 v[72:75], v[72:75], v[190:193], v[76:79]
	v_rcp_f32_e32 v207, v218
	v_rcp_f32_e32 v213, v219
	v_rcp_f32_e32 v223, v220
	v_rcp_f32_e32 v225, v221
	s_waitcnt vmcnt(17)
	v_mfma_f32_16x16x32_bf16 v[80:83], v[68:71], v[186:189], v[80:83]
	v_pk_mul_f32 v[198:199], v[206:207], v[198:199]
	v_pk_mul_f32 v[200:201], v[212:213], v[200:201]
	v_pk_mul_f32 v[202:203], v[222:223], v[202:203]
	v_pk_mul_f32 v[204:205], v[224:225], v[204:205]
	s_waitcnt lgkmcnt(0)
	v_mfma_f32_16x16x32_bf16 v[68:71], v[68:71], v[194:197], v[72:75]
	s_nop 5
	v_mul_f32_e32 v80, 0x3db504f3, v80
	s_nop 0
	v_mul_f32_e32 v68, 0x3db504f3, v68
	v_mul_f32_e32 v76, 0x3db504f3, v81
	ds_write2_b32 v142, v80, v68 offset1:16
	v_mul_f32_e32 v68, 0x3db504f3, v69
	v_mul_f32_e32 v77, 0x3db504f3, v82
	ds_write2_b32 v142, v76, v68 offset0:65 offset1:81
	v_mul_f32_e32 v68, 0x3db504f3, v70
	v_mul_f32_e32 v78, 0x3db504f3, v83
	ds_write2_b32 v142, v77, v68 offset0:130 offset1:146
	v_mul_f32_e32 v68, 0x3db504f3, v71
	ds_write2_b32 v142, v78, v68 offset0:195 offset1:211
	v_lshl_add_u32 v68, v159, 2, s43
	v_add3_u32 v165, v68, v158, s8
	v_mov_b32_e32 v68, v165
	ds_read2_b32 v[74:75], v68 offset1:1
	ds_read2_b32 v[72:73], v68 offset0:2 offset1:3
	ds_read2_b32 v[70:71], v68 offset0:4 offset1:5
	ds_read2_b32 v[68:69], v68 offset0:6 offset1:7
	s_waitcnt lgkmcnt(3)
	v_pk_mul_f32 v[76:77], v[74:75], v[74:75]
	s_waitcnt lgkmcnt(2)
	v_pk_mul_f32 v[78:79], v[72:73], v[72:73]
	v_add_f32_e32 v76, v76, v77
	v_add_f32_e32 v76, v76, v78
	s_waitcnt lgkmcnt(1)
	v_pk_mul_f32 v[80:81], v[70:71], v[70:71]
	v_add_f32_e32 v76, v76, v79
	v_add_f32_e32 v76, v76, v80
	s_waitcnt lgkmcnt(0)
	v_pk_mul_f32 v[82:83], v[68:69], v[68:69]
	v_add_f32_e32 v76, v76, v81
	v_add_f32_e32 v76, v76, v82
	v_add_f32_e32 v76, v76, v83
	s_nop 1
	v_add_f32_dpp v76, v76, v76 quad_perm:[1,0,3,2] row_mask:0xf bank_mask:0xf bound_ctrl:1
	s_nop 1
	v_add_f32_dpp v76, v76, v76 quad_perm:[2,3,0,1] row_mask:0xf bank_mask:0xf bound_ctrl:1
	s_nop 1
	v_mov_b32_dpp v77, v76 row_half_mirror row_mask:0xf bank_mask:0xf bound_ctrl:1
	s_and_saveexec_b64 s[8:9], s[4:5]
	s_cbranch_execz .LBB0_1088
	v_add_f32_e32 v78, v76, v77
	s_nop 1
	s_add_u32 s44, s6, 0x1a900000
	s_addc_u32 s45, s7, 0
	global_store_dword v120, v78, s[44:45]
.LBB0_1088:
	s_or_b64 exec, exec, s[8:9]
	s_waitcnt vmcnt(16)
	v_pk_mul_f32 v[74:75], v[20:21], v[74:75]
	v_pk_mul_f32 v[72:73], v[22:23], v[72:73]
	v_pk_mul_f32 v[70:71], v[16:17], v[70:71]
	s_mov_b64 s[8:9], 0x2000
	v_pk_mul_f32 v[68:69], v[18:19], v[68:69]
	v_lshl_add_u64 v[142:143], v[132:133], 0, s[8:9]
	v_lshl_add_u64 v[132:133], s[6:7], 0, v[122:123]
	s_mov_b32 s8, 0x12800000
	s_bitcmp1_b32 s31, 0
	v_pk_mul_f32 v[74:75], v[198:199], v[74:75]
	v_pk_mul_f32 v[72:73], v[200:201], v[72:73]
	v_pk_mul_f32 v[70:71], v[202:203], v[70:71]
	v_pk_mul_f32 v[68:69], v[204:205], v[68:69]
	v_cvt_pk_bf16_f32 v40, v74, v75
	v_cvt_pk_bf16_f32 v41, v72, v73
	v_cvt_pk_bf16_f32 v42, v70, v71
	v_cvt_pk_bf16_f32 v43, v68, v69
	s_cselect_b32 s8, 0x6c00, 0
	s_nop 0
	s_add_u32 s44, s6, 0x12800000
	s_addc_u32 s45, s7, 0
	global_store_dwordx4 v122, v[40:43], s[44:45]
	s_waitcnt lgkmcnt(0)
	s_barrier
	s_nop 0
	v_add_u32_e32 v40, s8, v148
	ds_write_b128 v40, v[44:47]
	ds_write_b128 v40, v[48:51] offset:9216
	ds_write_b128 v40, v[52:55] offset:18432
	s_mov_b32 s8, 0x40000
	s_nop 0
	s_add_u32 s44, s6, 0x4000
	s_addc_u32 s45, s7, 0
	global_load_dwordx4 v[44:47], v124, s[44:45]
	s_nop 1
	s_add_u32 s44, s6, 0x6000
	s_addc_u32 s45, s7, 0
	global_load_dwordx4 v[48:51], v124, s[44:45]
	s_mov_b32 s8, 0xb410000
	s_nop 0
	s_add_u32 s44, s6, 0x40000
	s_addc_u32 s45, s7, 0
	global_load_dwordx4 v[52:55], v126, s[44:45]
	s_mul_i32 s8, s40, 0x4400
	s_nop 0
	s_add_u32 s44, s6, 0xb410000
	s_addc_u32 s45, s7, 0
	global_load_dwordx4 v[80:83], v128, s[44:45]
	global_load_dwordx4 v[76:79], v128, s[44:45] offset:64
	global_load_dwordx4 v[72:75], v128, s[44:45] offset:128
	global_load_dwordx4 v[68:71], v128, s[44:45] offset:192
	s_nop 1
	s_add_u32 s44, s6, 0x4000
	s_addc_u32 s45, s7, 0
	global_load_dwordx4 v[40:43], v130, s[44:45]
	ds_read_b128 v[166:169], v161 offset:512
	ds_read_b128 v[170:173], v161 offset:544
	ds_read_b128 v[174:177], v161 offset:576
	ds_read_b128 v[178:181], v161 offset:608
	s_waitcnt lgkmcnt(3)
	v_pk_mul_f32 v[0:1], v[0:1], v[166:167]
	v_mov_b32_e32 v166, s41
	s_waitcnt lgkmcnt(1)
	v_pk_mul_f32 v[10:11], v[10:11], v[176:177]
	s_waitcnt lgkmcnt(0)
	v_pk_mul_f32 v[14:15], v[14:15], v[180:181]
	v_pk_mul_f32 v[6:7], v[6:7], v[172:173]
	v_pk_mul_f32 v[2:3], v[2:3], v[168:169]
	v_pk_mul_f32 v[12:13], v[12:13], v[178:179]
	v_pk_mul_f32 v[8:9], v[8:9], v[174:175]
	v_pk_mul_f32 v[4:5], v[4:5], v[170:171]
	s_nop 0
	v_add_u32_e32 v190, v166, v147
	v_add_u32_e32 v194, v166, v145
	ds_read_b128 v[166:169], v190
	ds_read_b128 v[170:173], v190 offset:32
	ds_read_b128 v[174:177], v194 offset:18432
	ds_read_b128 v[178:181], v194 offset:18464
	ds_read_b128 v[182:185], v190 offset:64
	ds_read_b128 v[186:189], v194 offset:18496
	ds_read_b128 v[190:193], v190 offset:96
	ds_read_b128 v[194:197], v194 offset:18528
	s_waitcnt lgkmcnt(5)
	v_mfma_f32_32x32x16_bf16 v[0:15], v[166:169], v[174:177], v[0:15]
	s_waitcnt vmcnt(15)
	v_lshlrev_b32_e32 v198, 16, v36
	v_lshlrev_b32_e32 v200, 16, v37
	v_lshlrev_b32_e32 v202, 16, v38
	v_lshlrev_b32_e32 v204, 16, v39
	v_add_u32_e32 v166, s8, v151
	s_waitcnt lgkmcnt(4)
	v_mfma_f32_32x32x16_bf16 v[0:15], v[170:173], v[178:181], v[0:15]
	v_and_b32_e32 v199, 0xffff0000, v36
	v_and_b32_e32 v201, 0xffff0000, v37
	v_and_b32_e32 v203, 0xffff0000, v38
	v_and_b32_e32 v205, 0xffff0000, v39
	v_add_u32_e32 v170, 0x6000, v166
	s_waitcnt lgkmcnt(2)
	v_mfma_f32_32x32x16_bf16 v[0:15], v[182:185], v[186:189], v[0:15]
	v_mul_f32_e32 v214, 0xbfb8aa3b, v198
	v_mul_f32_e32 v215, 0xbfb8aa3b, v200
	v_mul_f32_e32 v216, 0xbfb8aa3b, v202
	v_mul_f32_e32 v217, 0xbfb8aa3b, v204
	s_waitcnt lgkmcnt(0)
	v_mfma_f32_32x32x16_bf16 v[0:15], v[190:193], v[194:197], v[0:15]
	v_mul_f32_e32 v218, 0xbfb8aa3b, v199
	v_mul_f32_e32 v219, 0xbfb8aa3b, v201
	v_mul_f32_e32 v220, 0xbfb8aa3b, v203
	v_mul_f32_e32 v221, 0xbfb8aa3b, v205
	s_nop 11
	v_cvt_pk_bf16_f32 v166, v0, v1
	v_cvt_pk_bf16_f32 v167, v2, v3
	v_cvt_pk_bf16_f32 v168, v4, v5
	v_cvt_pk_bf16_f32 v169, v6, v7
	ds_write2_b64 v170, v[166:167], v[168:169] offset1:2
	v_cvt_pk_bf16_f32 v166, v8, v9
	v_cvt_pk_bf16_f32 v167, v10, v11
	v_cvt_pk_bf16_f32 v168, v12, v13
	v_cvt_pk_bf16_f32 v169, v14, v15
	ds_write2_b64 v170, v[166:167], v[168:169] offset0:4 offset1:6
	v_add_u32_e32 v166, s42, v155
	v_add_u32_e32 v194, 0x6000, v166
	ds_read_b128 v[166:169], v194
	ds_read_b128 v[170:173], v194 offset:4352
	ds_read_b128 v[174:177], v194 offset:64
	ds_read_b128 v[178:181], v194 offset:4416
	ds_read_b128 v[182:185], v194 offset:128
	ds_read_b128 v[186:189], v194 offset:4480
	ds_read_b128 v[190:193], v194 offset:192
	ds_read_b128 v[194:197], v194 offset:4544
	s_waitcnt vmcnt(21) lgkmcnt(7)
	v_mfma_f32_16x16x32_bf16 v[166:169], v[92:95], v[166:169], 0
	v_exp_f32_e32 v214, v214
	v_exp_f32_e32 v215, v215
	v_exp_f32_e32 v216, v216
	v_exp_f32_e32 v217, v217
	s_add_i32 s8, s26, s43
	s_mulk_i32 s40, 0x4100
	s_waitcnt lgkmcnt(6)
	v_mfma_f32_16x16x32_bf16 v[92:95], v[92:95], v[170:173], 0
	v_exp_f32_e32 v218, v218
	v_exp_f32_e32 v219, v219
	v_exp_f32_e32 v220, v220
	v_exp_f32_e32 v221, v221
	s_waitcnt vmcnt(20) lgkmcnt(5)
	v_mfma_f32_16x16x32_bf16 v[166:169], v[96:99], v[174:177], v[166:169]
	v_add_f32_e32 v214, 1.0, v214
	v_add_f32_e32 v215, 1.0, v215
	v_add_f32_e32 v216, 1.0, v216
	v_add_f32_e32 v217, 1.0, v217
	s_waitcnt lgkmcnt(4)
	v_mfma_f32_16x16x32_bf16 v[92:95], v[96:99], v[178:181], v[92:95]
	v_add_f32_e32 v218, 1.0, v218
	v_add_f32_e32 v219, 1.0, v219
	v_add_f32_e32 v220, 1.0, v220
	v_add_f32_e32 v221, 1.0, v221
	s_waitcnt vmcnt(19) lgkmcnt(3)
	v_mfma_f32_16x16x32_bf16 v[96:99], v[88:91], v[182:185], v[166:169]
	v_rcp_f32_e32 v206, v214
	v_rcp_f32_e32 v212, v215
	v_rcp_f32_e32 v222, v216
	v_rcp_f32_e32 v224, v217
	s_waitcnt lgkmcnt(2)
	v_mfma_f32_16x16x32_bf16 v[88:91], v[88:91], v[186:189], v[92:95]
	v_rcp_f32_e32 v207, v218
	v_rcp_f32_e32 v213, v219
	v_rcp_f32_e32 v223, v220
	v_rcp_f32_e32 v225, v221
	s_nop 1
	v_lshl_add_u32 v166, v156, 2, s8
	s_mov_b32 s8, 0xe800
	v_add3_u32 v166, v166, v154, s8
	s_waitcnt vmcnt(18) lgkmcnt(1)
	v_mfma_f32_16x16x32_bf16 v[96:99], v[84:87], v[190:193], v[96:99]
	v_pk_mul_f32 v[198:199], v[206:207], v[198:199]
	v_pk_mul_f32 v[200:201], v[212:213], v[200:201]
	v_pk_mul_f32 v[202:203], v[222:223], v[202:203]
	v_pk_mul_f32 v[204:205], v[224:225], v[204:205]
	s_waitcnt lgkmcnt(0)
	v_mfma_f32_16x16x32_bf16 v[84:87], v[84:87], v[194:197], v[88:91]
	s_nop 5
	v_mul_f32_e32 v96, 0x3db504f3, v96
	s_nop 0
	v_mul_f32_e32 v84, 0x3db504f3, v84
	v_mul_f32_e32 v92, 0x3db504f3, v97
	ds_write2_b32 v166, v96, v84 offset1:16
	v_mul_f32_e32 v84, 0x3db504f3, v85
	v_mul_f32_e32 v93, 0x3db504f3, v98
	ds_write2_b32 v166, v92, v84 offset0:65 offset1:81
	v_mul_f32_e32 v84, 0x3db504f3, v86
	v_mul_f32_e32 v94, 0x3db504f3, v99
	ds_write2_b32 v166, v93, v84 offset0:130 offset1:146
	v_mul_f32_e32 v84, 0x3db504f3, v87
	ds_write2_b32 v166, v94, v84 offset0:195 offset1:211
	v_add_u32_e32 v84, s40, v160
	v_add_u32_e32 v84, 0xe800, v84
	ds_read2_b32 v[92:93], v84 offset1:1
	ds_read2_b32 v[90:91], v84 offset0:2 offset1:3
	ds_read2_b32 v[88:89], v84 offset0:4 offset1:5
	ds_read2_b32 v[86:87], v84 offset0:6 offset1:7
	s_waitcnt lgkmcnt(3)
	v_pk_mul_f32 v[84:85], v[92:93], v[92:93]
	s_waitcnt lgkmcnt(2)
	v_pk_mul_f32 v[94:95], v[90:91], v[90:91]
	v_add_f32_e32 v84, v84, v85
	v_add_f32_e32 v84, v84, v94
	s_waitcnt lgkmcnt(1)
	v_pk_mul_f32 v[96:97], v[88:89], v[88:89]
	v_add_f32_e32 v84, v84, v95
	v_add_f32_e32 v84, v84, v96
	s_waitcnt lgkmcnt(0)
	v_pk_mul_f32 v[98:99], v[86:87], v[86:87]
	v_add_f32_e32 v84, v84, v97
	v_add_f32_e32 v84, v84, v98
	v_add_f32_e32 v84, v84, v99
	s_nop 1
	v_add_f32_dpp v84, v84, v84 quad_perm:[1,0,3,2] row_mask:0xf bank_mask:0xf bound_ctrl:1
	s_nop 1
	v_add_f32_dpp v84, v84, v84 quad_perm:[2,3,0,1] row_mask:0xf bank_mask:0xf bound_ctrl:1
	s_nop 1
	v_mov_b32_dpp v85, v84 row_half_mirror row_mask:0xf bank_mask:0xf bound_ctrl:1
	s_and_saveexec_b64 s[8:9], s[4:5]
	s_cbranch_execz .LBB0_1090
	v_add_f32_e32 v94, v84, v85
	s_nop 1
	s_add_u32 s44, s6, 0x1a901000
	s_addc_u32 s45, s7, 0
	global_store_dword v120, v94, s[44:45]
.LBB0_1090:
	s_or_b64 exec, exec, s[8:9]
	s_waitcnt vmcnt(17)
	v_pk_mul_f32 v[92:93], v[20:21], v[92:93]
	v_pk_mul_f32 v[90:91], v[22:23], v[90:91]
	v_pk_mul_f32 v[88:89], v[16:17], v[88:89]
	s_mov_b64 s[8:9], 0x40000
	v_pk_mul_f32 v[86:87], v[18:19], v[86:87]
	v_lshl_add_u64 v[84:85], v[138:139], 0, s[8:9]
	s_mov_b32 s8, 0x12840000
	s_mulk_i32 s39, 0x6c00
	s_mov_b64 s[40:41], 0x4000
	v_lshl_add_u64 v[94:95], v[142:143], 0, s[40:41]
	v_lshl_add_u64 v[138:139], v[140:141], 0, s[40:41]
	v_pk_mul_f32 v[92:93], v[198:199], v[92:93]
	v_pk_mul_f32 v[90:91], v[200:201], v[90:91]
	v_pk_mul_f32 v[88:89], v[202:203], v[88:89]
	v_pk_mul_f32 v[86:87], v[204:205], v[86:87]
	v_cvt_pk_bf16_f32 v36, v92, v93
	v_cvt_pk_bf16_f32 v37, v90, v91
	v_cvt_pk_bf16_f32 v38, v88, v89
	v_cvt_pk_bf16_f32 v39, v86, v87
	s_mov_b32 s8, 0x40000
	s_nop 0
	s_add_u32 s44, s6, 0x12840000
	s_addc_u32 s45, s7, 0
	global_store_dwordx4 v122, v[36:39], s[44:45]
	s_waitcnt lgkmcnt(0)
	s_barrier
	s_nop 0
	v_add_u32_e32 v36, s39, v148
	ds_write_b128 v36, v[56:59]
	ds_write_b128 v36, v[60:63] offset:9216
	ds_write_b128 v36, v[64:67] offset:18432
	s_nop 1
	s_add_u32 s44, s6, 0x8000
	s_addc_u32 s45, s7, 0
	global_load_dwordx4 v[56:59], v124, s[44:45]
	s_nop 1
	s_add_u32 s44, s6, 0xa000
	s_addc_u32 s45, s7, 0
	global_load_dwordx4 v[60:63], v124, s[44:45]
	s_mov_b32 s8, 0xb414000
	s_nop 0
	s_add_u32 s44, s6, 0x80000
	s_addc_u32 s45, s7, 0
	global_load_dwordx4 v[64:67], v126, s[44:45]
	s_nop 1
	s_add_u32 s44, s6, 0xb414000
	s_addc_u32 s45, s7, 0
	global_load_dwordx4 v[92:95], v128, s[44:45]
	global_load_dwordx4 v[96:99], v128, s[44:45] offset:64
	global_load_dwordx4 v[88:91], v128, s[44:45] offset:128
	global_load_dwordx4 v[84:87], v128, s[44:45] offset:192
	s_nop 1
	s_add_u32 s44, s6, 0x8000
	s_addc_u32 s45, s7, 0
	global_load_dwordx4 v[36:39], v130, s[44:45]
	ds_read_b128 v[136:139], v161 offset:1024
	ds_read_b128 v[140:143], v161 offset:1056
	ds_read_b128 v[166:169], v161 offset:1088
	ds_read_b128 v[170:173], v161 offset:1120
	s_waitcnt lgkmcnt(3)
	v_pk_mul_f32 v[0:1], v[0:1], v[136:137]
	v_mov_b32_e32 v136, s38
	s_waitcnt lgkmcnt(1)
	v_pk_mul_f32 v[10:11], v[10:11], v[168:169]
	s_waitcnt lgkmcnt(0)
	v_pk_mul_f32 v[14:15], v[14:15], v[172:173]
	v_pk_mul_f32 v[6:7], v[6:7], v[142:143]
	v_pk_mul_f32 v[2:3], v[2:3], v[138:139]
	v_pk_mul_f32 v[12:13], v[12:13], v[170:171]
	v_pk_mul_f32 v[8:9], v[8:9], v[166:167]
	v_pk_mul_f32 v[4:5], v[4:5], v[140:141]
	s_nop 0
	v_add_u32_e32 v182, v136, v147
	v_add_u32_e32 v186, v136, v145
	ds_read_b128 v[136:139], v182
	ds_read_b128 v[140:143], v182 offset:32
	ds_read_b128 v[166:169], v186 offset:18432
	ds_read_b128 v[170:173], v186 offset:18464
	ds_read_b128 v[174:177], v182 offset:64
	ds_read_b128 v[178:181], v186 offset:18496
	ds_read_b128 v[182:185], v182 offset:96
	ds_read_b128 v[186:189], v186 offset:18528
	s_waitcnt lgkmcnt(5)
	v_mfma_f32_32x32x16_bf16 v[0:15], v[136:139], v[166:169], v[0:15]
	s_waitcnt vmcnt(16)
	v_lshlrev_b32_e32 v198, 16, v100
	v_lshlrev_b32_e32 v200, 16, v101
	v_lshlrev_b32_e32 v202, 16, v102
	v_lshlrev_b32_e32 v204, 16, v103
	s_waitcnt lgkmcnt(4)
	v_mfma_f32_32x32x16_bf16 v[0:15], v[140:143], v[170:173], v[0:15]
	v_and_b32_e32 v199, 0xffff0000, v100
	v_and_b32_e32 v201, 0xffff0000, v101
	v_and_b32_e32 v203, 0xffff0000, v102
	v_and_b32_e32 v205, 0xffff0000, v103
	s_waitcnt lgkmcnt(2)
	v_mfma_f32_32x32x16_bf16 v[0:15], v[174:177], v[178:181], v[0:15]
	v_mul_f32_e32 v214, 0xbfb8aa3b, v198
	v_mul_f32_e32 v215, 0xbfb8aa3b, v200
	v_mul_f32_e32 v216, 0xbfb8aa3b, v202
	v_mul_f32_e32 v217, 0xbfb8aa3b, v204
	s_waitcnt lgkmcnt(0)
	v_mfma_f32_32x32x16_bf16 v[0:15], v[182:185], v[186:189], v[0:15]
	v_mul_f32_e32 v218, 0xbfb8aa3b, v199
	v_mul_f32_e32 v219, 0xbfb8aa3b, v201
	v_mul_f32_e32 v220, 0xbfb8aa3b, v203
	v_mul_f32_e32 v221, 0xbfb8aa3b, v205
	s_nop 11
	v_cvt_pk_bf16_f32 v136, v0, v1
	v_cvt_pk_bf16_f32 v137, v2, v3
	v_cvt_pk_bf16_f32 v138, v4, v5
	v_cvt_pk_bf16_f32 v139, v6, v7
	ds_write2_b64 v162, v[136:137], v[138:139] offset1:2
	v_cvt_pk_bf16_f32 v136, v8, v9
	v_cvt_pk_bf16_f32 v137, v10, v11
	v_cvt_pk_bf16_f32 v138, v12, v13
	v_cvt_pk_bf16_f32 v139, v14, v15
	ds_write2_b64 v162, v[136:137], v[138:139] offset0:4 offset1:6
	ds_read_b128 v[136:139], v164
	ds_read_b128 v[140:143], v164 offset:4352
	ds_read_b128 v[166:169], v164 offset:64
	ds_read_b128 v[170:173], v164 offset:4416
	ds_read_b128 v[174:177], v164 offset:128
	ds_read_b128 v[178:181], v164 offset:4480
	ds_read_b128 v[182:185], v164 offset:192
	ds_read_b128 v[186:189], v164 offset:4544
	s_waitcnt vmcnt(23) lgkmcnt(7)
	v_mfma_f32_16x16x32_bf16 v[136:139], v[116:119], v[136:139], 0
	v_exp_f32_e32 v214, v214
	v_exp_f32_e32 v215, v215
	v_exp_f32_e32 v216, v216
	v_exp_f32_e32 v217, v217
	s_waitcnt lgkmcnt(6)
	v_mfma_f32_16x16x32_bf16 v[116:119], v[116:119], v[140:143], 0
	v_exp_f32_e32 v218, v218
	v_exp_f32_e32 v219, v219
	v_exp_f32_e32 v220, v220
	v_exp_f32_e32 v221, v221
	s_waitcnt vmcnt(22) lgkmcnt(5)
	v_mfma_f32_16x16x32_bf16 v[136:139], v[112:115], v[166:169], v[136:139]
	v_add_f32_e32 v214, 1.0, v214
	v_add_f32_e32 v215, 1.0, v215
	v_add_f32_e32 v216, 1.0, v216
	v_add_f32_e32 v217, 1.0, v217
	s_waitcnt lgkmcnt(4)
	v_mfma_f32_16x16x32_bf16 v[112:115], v[112:115], v[170:173], v[116:119]
	v_add_f32_e32 v218, 1.0, v218
	v_add_f32_e32 v219, 1.0, v219
	v_add_f32_e32 v220, 1.0, v220
	v_add_f32_e32 v221, 1.0, v221
	s_waitcnt vmcnt(21) lgkmcnt(3)
	v_mfma_f32_16x16x32_bf16 v[116:119], v[108:111], v[174:177], v[136:139]
	v_rcp_f32_e32 v206, v214
	v_rcp_f32_e32 v212, v215
	v_rcp_f32_e32 v222, v216
	v_rcp_f32_e32 v224, v217
	s_waitcnt lgkmcnt(2)
	v_mfma_f32_16x16x32_bf16 v[108:111], v[108:111], v[178:181], v[112:115]
	v_rcp_f32_e32 v207, v218
	v_rcp_f32_e32 v213, v219
	v_rcp_f32_e32 v223, v220
	v_rcp_f32_e32 v225, v221
	s_waitcnt vmcnt(20) lgkmcnt(1)
	v_mfma_f32_16x16x32_bf16 v[116:119], v[104:107], v[182:185], v[116:119]
	v_pk_mul_f32 v[198:199], v[206:207], v[198:199]
	v_pk_mul_f32 v[200:201], v[212:213], v[200:201]
	v_pk_mul_f32 v[202:203], v[222:223], v[202:203]
	v_pk_mul_f32 v[204:205], v[224:225], v[204:205]
	s_waitcnt lgkmcnt(0)
	v_mfma_f32_16x16x32_bf16 v[104:107], v[104:107], v[186:189], v[108:111]
	s_nop 5
	v_mul_f32_e32 v116, 0x3db504f3, v116
	s_nop 0
	v_mul_f32_e32 v104, 0x3db504f3, v104
	v_mul_f32_e32 v112, 0x3db504f3, v117
	ds_write2_b32 v163, v116, v104 offset1:16
	v_mul_f32_e32 v104, 0x3db504f3, v105
	v_mul_f32_e32 v113, 0x3db504f3, v118
	ds_write2_b32 v163, v112, v104 offset0:65 offset1:81
	v_mul_f32_e32 v104, 0x3db504f3, v106
	v_mul_f32_e32 v114, 0x3db504f3, v119
	ds_write2_b32 v163, v113, v104 offset0:130 offset1:146
	v_mul_f32_e32 v104, 0x3db504f3, v107
	ds_write2_b32 v163, v114, v104 offset0:195 offset1:211
	ds_read2_b32 v[110:111], v165 offset1:1
	ds_read2_b32 v[108:109], v165 offset0:2 offset1:3
	ds_read2_b32 v[106:107], v165 offset0:4 offset1:5
	ds_read2_b32 v[104:105], v165 offset0:6 offset1:7
	s_waitcnt lgkmcnt(3)
	v_pk_mul_f32 v[112:113], v[110:111], v[110:111]
	s_waitcnt lgkmcnt(2)
	v_pk_mul_f32 v[114:115], v[108:109], v[108:109]
	v_add_f32_e32 v112, v112, v113
	v_add_f32_e32 v112, v112, v114
	s_waitcnt lgkmcnt(1)
	v_pk_mul_f32 v[116:117], v[106:107], v[106:107]
	v_add_f32_e32 v112, v112, v115
	v_add_f32_e32 v112, v112, v116
	s_waitcnt lgkmcnt(0)
	v_pk_mul_f32 v[118:119], v[104:105], v[104:105]
	v_add_f32_e32 v112, v112, v117
	v_add_f32_e32 v112, v112, v118
	v_add_f32_e32 v112, v112, v119
	s_nop 1
	v_add_f32_dpp v112, v112, v112 quad_perm:[1,0,3,2] row_mask:0xf bank_mask:0xf bound_ctrl:1
	s_nop 1
	v_add_f32_dpp v112, v112, v112 quad_perm:[2,3,0,1] row_mask:0xf bank_mask:0xf bound_ctrl:1
	s_nop 1
	v_mov_b32_dpp v113, v112 row_half_mirror row_mask:0xf bank_mask:0xf bound_ctrl:1
	s_and_saveexec_b64 s[8:9], s[4:5]
	s_cbranch_execz .LBB0_1085
	v_add_f32_e32 v114, v112, v113
	s_nop 1
	s_add_u32 s44, s6, 0x1a902000
	s_addc_u32 s45, s7, 0
	global_store_dword v120, v114, s[44:45]
	s_branch .LBB0_1085
